# ctx-query attention units on RG workgroups 64..127 + dt pass always spread
# speedup vs baseline: 1.0016x; 1.0011x over previous
.LBB0_692:
	s_and_b64 vcc, exec, s[4:5]
	s_cbranch_vccz .LBB0_783
	s_and_b32 s0, s22, 0x7fffffc0
	s_cmpk_lg_i32 s0, 0x140
	s_mov_b64 s[4:5], -1
	s_cbranch_scc0 .LBB0_745
	s_cmpk_lt_u32 s22, 0x200
	s_cbranch_scc1 .LBB0_744
	s_add_i32 s0, s22, 0xfffffe00
	v_mbcnt_lo_u32_b32 v0, -1, 0
	v_mbcnt_hi_u32_b32 v0, -1, v0
	s_lshr_b32 s4, s0, 5
	v_add_u32_e32 v36, s93, v0
	s_lshl_b32 s0, s22, 8
	s_lshl_b32 s12, s4, 11
	v_readfirstlane_b32 s2, v36
	s_and_b32 s0, s0, 0x700
	s_ashr_i32 s5, s2, 6
	s_or_b32 s0, s12, s0
	s_lshl_b32 s2, s5, 5
	v_readlane_b32 s8, v255, 11
	v_and_b32_e32 v0, 31, v36
	s_add_i32 s0, s2, s0
	v_readlane_b32 s9, v255, 12
	s_bfe_u32 s1, s22, 0x20003
	v_or_b32_e32 v4, s0, v0
	v_mov_b64_e32 v[2:3], s[8:9]
	v_bfe_u32 v37, v36, 5, 1
	v_mad_i64_i32 v[2:3], s[2:3], v4, s72, v[2:3]
	s_lshl_b32 s36, s1, 8
	v_lshl_add_u64 v[2:3], v[2:3], 0, s[36:37]
	v_lshlrev_b32_e32 v34, 4, v37
	v_mov_b32_e32 v35, v1
	v_lshl_add_u64 v[30:31], v[2:3], 0, v[34:35]
	global_load_dwordx4 v[2:5], v[30:31], off offset:2560
	global_load_dwordx4 v[6:9], v[30:31], off offset:2592
	global_load_dwordx4 v[10:13], v[30:31], off offset:2624
	global_load_dwordx4 v[14:17], v[30:31], off offset:2656
	global_load_dwordx4 v[18:21], v[30:31], off offset:2688
	global_load_dwordx4 v[22:25], v[30:31], off offset:2720
	global_load_dwordx4 v[26:29], v[30:31], off offset:2752
	s_nop 0
	global_load_dwordx4 v[30:33], v[30:31], off offset:2784
	v_lshlrev_b32_e32 v35, 4, v36
	v_and_b32_e32 v42, 0xf0, v35
	s_movk_i32 s6, 0x60
	v_bitop3_b32 v215, v34, v42, s6 bitop3:0x36
	s_movk_i32 s6, 0x80
	v_bitop3_b32 v216, v34, v42, s6 bitop3:0x36
	s_movk_i32 s6, 0xa0
	v_bitop3_b32 v217, v34, v42, s6 bitop3:0x36
	s_movk_i32 s6, 0xc0
	s_lshl_b32 s2, s5, 9
	s_lshl_b32 s3, s5, 13
	v_bitop3_b32 v218, v34, v42, s6 bitop3:0x36
	s_movk_i32 s6, 0xe0
	s_lshl_b32 s13, s4, 8
	v_bfe_u32 v38, v36, 4, 2
	v_bfe_u32 v39, v36, 2, 3
	v_bitop3_b32 v219, v34, v42, s6 bitop3:0x36
	s_lshl_b32 s6, s5, 3
	s_add_i32 s15, s3, 0
	s_add_i32 s14, s2, 0
	s_lshl_b32 s1, s1, 7
	s_add_i32 s13, s13, 0x8000
	v_lshlrev_b32_e32 v41, 3, v36
	v_or_b32_e32 v43, s6, v38
	v_or_b32_e32 v39, s6, v39
	s_add_i32 s15, s15, 0x11000
	s_add_i32 s14, s14, 0x10000
	s_movk_i32 s2, 0xb00
	v_and_b32_e32 v40, 32, v36
	v_lshlrev_b32_e32 v212, 8, v0
	v_bitop3_b32 v0, v37, v36, 15 bitop3:0x78
	v_and_b32_e32 v37, 24, v41
	v_bitop3_b32 v38, s6, v36, v38 bitop3:0x36
	v_mul_lo_u32 v39, v39, s2
	v_mul_lo_u32 v44, v43, s2
	v_bitop3_b32 v43, v43, v36, 4 bitop3:0x36
	s_add_u32 s36, s8, s36
	v_lshlrev_b32_e32 v38, 3, v38
	v_or3_b32 v37, v40, v37, v39
	s_movk_i32 s2, 0x78
	v_lshlrev_b32_e32 v39, 3, v43
	s_addc_u32 s38, s9, 0
	s_mul_i32 s4, s4, 0xb00000
	v_and_or_b32 v38, v38, s2, v44
	v_lshlrev_b32_e32 v196, 1, v37
	v_and_or_b32 v37, v39, s2, v44
	s_mul_hi_u32 s3, s12, 0x1600
	s_add_u32 s2, s36, s4
	v_add_u32_e32 v45, s15, v212
	s_addc_u32 s3, s38, s3
	s_lshl_b32 s6, s5, 11
	v_bitop3_b32 v213, v34, v42, 32 bitop3:0x36
	v_bitop3_b32 v214, v34, v42, 64 bitop3:0x36
	v_lshl_add_u32 v40, v0, 4, v45
	v_lshlrev_b32_e32 v0, 1, v38
	s_add_u32 s4, s2, 0x1200
	v_add_u32_e32 v43, v45, v213
	v_add_u32_e32 v46, v45, v214
	v_add_u32_e32 v47, v45, v215
	v_add_u32_e32 v48, v45, v216
	v_add_u32_e32 v49, v45, v217
	v_add_u32_e32 v50, v45, v218
	v_add_u32_e32 v45, v45, v219
	s_waitcnt vmcnt(7)
	ds_write_b128 v40, v[2:5]
	s_waitcnt vmcnt(6)
	ds_write_b128 v43, v[6:9]
	s_waitcnt vmcnt(5)
	ds_write_b128 v46, v[10:13]
	s_waitcnt vmcnt(4)
	ds_write_b128 v47, v[14:17]
	s_waitcnt vmcnt(3)
	ds_write_b128 v48, v[18:21]
	s_waitcnt vmcnt(2)
	ds_write_b128 v49, v[22:25]
	s_waitcnt vmcnt(1)
	ds_write_b128 v50, v[26:29]
	s_waitcnt vmcnt(0)
	ds_write_b128 v45, v[30:33]
	s_addc_u32 s5, s3, 0
	v_lshl_add_u64 v[2:3], s[2:3], 0, v[0:1]
	s_add_i32 s39, s6, 0
	v_lshl_add_u32 v198, v37, 1, v249
	v_lshl_add_u64 v[2:3], v[2:3], 0, s[26:27]
	s_add_i32 m0, s39, 0x8000
	v_mov_b32_e32 v199, v1
	global_load_lds_dwordx4 v[2:3], off
	s_mov_b32 m0, s39
	v_lshl_add_u64 v[2:3], s[2:3], 0, v[198:199]
	global_load_lds_dwordx4 v196, s[4:5]
	v_lshl_add_u64 v[2:3], v[2:3], 0, s[26:27]
	s_add_i32 m0, s39, 0x8400
	v_or_b32_e32 v200, 0x80, v196
	global_load_lds_dwordx4 v[2:3], off
	s_add_i32 m0, s39, 0x400
	v_or_b32_e32 v2, 32, v34
	global_load_lds_dwordx4 v200, s[4:5]
	v_lshlrev_b32_e32 v9, 1, v36
	v_and_b32_e32 v11, 0x118, v41
	v_or_b32_e32 v3, 64, v34
	v_or_b32_e32 v4, 0x60, v34
	v_or_b32_e32 v5, 0x80, v34
	v_or_b32_e32 v6, 0xa0, v34
	v_or_b32_e32 v7, 0xc0, v34
	v_or_b32_e32 v8, 0xe0, v34
	v_and_b32_e32 v10, 0xc0, v35
	s_waitcnt vmcnt(0)
	s_movk_i32 s2, 0xf0
	v_bitop3_b32 v222, v2, v212, v42 bitop3:0xde
	v_and_or_b32 v2, v9, 32, v11
	v_mov_b32_e32 v16, v1
	v_mov_b32_e32 v17, v1
	v_bitop3_b32 v220, v34, v35, s2 bitop3:0x78
	v_bitop3_b32 v221, v34, v212, v42 bitop3:0xde
	v_bitop3_b32 v223, v3, v212, v42 bitop3:0xde
	v_bitop3_b32 v224, v4, v212, v42 bitop3:0xde
	v_bitop3_b32 v225, v5, v212, v42 bitop3:0xde
	v_bitop3_b32 v226, v6, v212, v42 bitop3:0xde
	v_bitop3_b32 v227, v7, v212, v42 bitop3:0xde
	v_bitop3_b32 v228, v8, v212, v42 bitop3:0xde
	v_add3_u32 v229, v10, 0, v2
	v_mov_b32_e32 v2, v1
	v_mov_b32_e32 v3, v1
	v_mov_b32_e32 v4, v1
	v_mov_b32_e32 v5, v1
	v_mov_b32_e32 v6, v1
	v_mov_b32_e32 v7, v1
	v_mov_b32_e32 v8, v1
	v_mov_b32_e32 v9, v1
	v_mov_b32_e32 v10, v1
	v_mov_b32_e32 v11, v1
	v_mov_b32_e32 v12, v1
	v_mov_b32_e32 v13, v1
	v_mov_b32_e32 v14, v1
	v_mov_b32_e32 v15, v1
	v_mov_b64_e32 v[80:81], v[16:17]
	v_mov_b64_e32 v[48:49], v[16:17]
	v_mov_b64_e32 v[32:33], v[16:17]
	v_mov_b64_e32 v[128:129], v[16:17]
	v_mov_b64_e32 v[112:113], v[16:17]
	v_mov_b64_e32 v[96:97], v[16:17]
	v_mov_b64_e32 v[64:65], v[16:17]
	v_mov_b32_e32 v197, v1
	v_mov_b32_e32 v201, v1
	s_mov_b32 s40, 0
	v_mov_b32_e32 v202, v1
	v_mov_b32_e32 v203, v1
	v_mov_b32_e32 v231, 0
	s_mov_b64 s[4:5], 0
	s_mov_b64 s[6:7], -1
	v_mov_b64_e32 v[78:79], v[14:15]
	v_mov_b64_e32 v[76:77], v[12:13]
	v_mov_b64_e32 v[74:75], v[10:11]
	v_mov_b64_e32 v[72:73], v[8:9]
	v_mov_b64_e32 v[70:71], v[6:7]
	v_mov_b64_e32 v[68:69], v[4:5]
	v_mov_b64_e32 v[66:67], v[2:3]
	v_mov_b64_e32 v[46:47], v[14:15]
	v_mov_b64_e32 v[44:45], v[12:13]
	v_mov_b64_e32 v[42:43], v[10:11]
	v_mov_b64_e32 v[40:41], v[8:9]
	v_mov_b64_e32 v[38:39], v[6:7]
	v_mov_b64_e32 v[36:37], v[4:5]
	v_mov_b64_e32 v[34:35], v[2:3]
	v_mov_b64_e32 v[30:31], v[14:15]
	v_mov_b64_e32 v[28:29], v[12:13]
	v_mov_b64_e32 v[26:27], v[10:11]
	v_mov_b64_e32 v[24:25], v[8:9]
	v_mov_b64_e32 v[22:23], v[6:7]
	v_mov_b64_e32 v[20:21], v[4:5]
	v_mov_b64_e32 v[18:19], v[2:3]
	v_mov_b64_e32 v[126:127], v[14:15]
	v_mov_b64_e32 v[124:125], v[12:13]
	v_mov_b64_e32 v[122:123], v[10:11]
	v_mov_b64_e32 v[120:121], v[8:9]
	v_mov_b64_e32 v[118:119], v[6:7]
	v_mov_b64_e32 v[116:117], v[4:5]
	v_mov_b64_e32 v[114:115], v[2:3]
	v_mov_b64_e32 v[110:111], v[14:15]
	v_mov_b64_e32 v[108:109], v[12:13]
	v_mov_b64_e32 v[106:107], v[10:11]
	v_mov_b64_e32 v[104:105], v[8:9]
	v_mov_b64_e32 v[102:103], v[6:7]
	v_mov_b64_e32 v[100:101], v[4:5]
	v_mov_b64_e32 v[98:99], v[2:3]
	v_mov_b64_e32 v[94:95], v[14:15]
	v_mov_b64_e32 v[92:93], v[12:13]
	v_mov_b64_e32 v[90:91], v[10:11]
	v_mov_b64_e32 v[88:89], v[8:9]
	v_mov_b64_e32 v[86:87], v[6:7]
	v_mov_b64_e32 v[84:85], v[4:5]
	v_mov_b64_e32 v[82:83], v[2:3]
	v_mov_b64_e32 v[62:63], v[14:15]
	v_mov_b64_e32 v[60:61], v[12:13]
	v_mov_b64_e32 v[58:59], v[10:11]
	v_mov_b64_e32 v[56:57], v[8:9]
	v_mov_b64_e32 v[54:55], v[6:7]
	v_mov_b64_e32 v[52:53], v[4:5]
	v_mov_b64_e32 v[50:51], v[2:3]
	v_mov_b32_e32 v230, 0
	s_waitcnt vmcnt(0) lgkmcnt(0)
	s_barrier
	s_branch .LBB0_699
